# combo7 + mixer-C softmax VALU re-spaced so every MFMA gap carries 2 exp + 2 add + 1 cvt (last pair's adds+cvt carried into the next slot's first gap)
# baseline (speedup 1.0000x reference)
; #define LAS __attribute__((address_space(3)))
; __device__ __forceinline__ void attn_c_unit(LAS unsigned char* lds, const bf16_t* proj, const bf16_t* vt, bf16_t* obuf, int b, int hk, int blk, float mref, unsigned long long* sg) {
;     ...
;     f32x16 negm;
; #pragma unroll
;     for (int i = 0; i < 16; ++i) negm[i] = 0.f;
;     float l0 = 0.f, l1 = 0.f;
;     f32x16 o00, o01, o10, o11;
; #pragma unroll
;     for (int i = 0; i < 16; ++i) { o00[i] = 0.f; o01[i] = 0.f; o10[i] = 0.f; o11[i] = 0.f; }
;     const int pr = (r & ~12) | ((r & 4) << 1) | ((r & 8) >> 1);
;     constexpr int nT = SEQ / 64;
;     constexpr int CK = 0, CV = 4 * ATT_TILE;
; #pragma unroll
;     for (int i = 0; i < 2; ++i) { kreg = *(const u32x4*)(kg + (size_t)(i * 64) * INW); vreg = *(const u32x4*)(vg + i * 64);
;         *(LAS u32x4*)(lds + CK + i * ATT_TILE + sdst) = kreg; *(LAS u32x4*)(lds + CV + i * ATT_TILE + sdst) = vreg; }
;     __syncthreads();
;     for (int it = 0; it < nT; ++it) {
;         const int buf = it & 3;
;         if (it + 2 < nT) { kreg = *(const u32x4*)(kg + (size_t)((it + 2) * 64) * INW); vreg = *(const u32x4*)(vg + (it + 2) * 64); }
;         const LAS unsigned char* kb = lds + CK + buf * ATT_TILE + pr * KP + 16 * h;
;         f32x16 s00, s01, s10, s11;
;         {
;             const bf16x8 a0 = *(const LAS bf16x8*)(kb), a1 = *(const LAS bf16x8*)(kb + 32 * KP);
;             s00 = __builtin_amdgcn_mfma_f32_32x32x16_bf16(a0, qf[0][0], negm, 0, 0, 0);
;             s10 = __builtin_amdgcn_mfma_f32_32x32x16_bf16(a0, qf[1][0], negm, 0, 0, 0);
;             s01 = __builtin_amdgcn_mfma_f32_32x32x16_bf16(a1, qf[0][0], negm, 0, 0, 0);
;             s11 = __builtin_amdgcn_mfma_f32_32x32x16_bf16(a1, qf[1][0], negm, 0, 0, 0);
;         }
.LBB0_207:
	s_bfe_u32 s24, s11, 0x10002
	v_mov_b32_e32 v18, v199
	s_lshl_b32 s54, s24, 13
	v_ashrrev_i32_e32 v8, 3, v18
	v_add_u32_e32 v0, s54, v8
	v_mov_b64_e32 v[10:11], s[86:87]
	s_and_b32 s22, s11, 3
	s_waitcnt lgkmcnt(0)
	v_mad_i64_i32 v[0:1], s[12:13], v0, s25, v[10:11]
	s_mul_i32 s14, s24, 14
	s_lshl_b32 s12, s22, 7
	s_mov_b32 s13, s55
	v_lshlrev_b32_e32 v4, 4, v18
	s_add_i32 s15, s22, s14
	v_lshl_add_u64 v[0:1], v[0:1], 0, s[12:13]
	v_and_b32_e32 v128, 0x70, v4
	s_lshl_b32 s12, s15, 6
	v_lshl_add_u64 v[14:15], v[0:1], 0, v[128:129]
	v_ashrrev_i32_e32 v9, 31, v8
	s_addk_i32 s12, 0x280
	v_add_co_u32_e32 v0, vcc, s48, v14
	v_lshl_add_u64 v[2:3], s[12:13], 0, v[8:9]
	s_nop 0
	v_addc_co_u32_e32 v1, vcc, 0, v15, vcc
	s_mov_b32 s12, 0x79000
	v_add_co_u32_e32 v14, vcc, s12, v14
	s_and_b32 s12, s10, 3
	s_add_i32 s14, s14, s12
	s_lshl_b32 s13, s14, 6
	s_add_i32 s14, s13, 0x280
	s_lshl_b32 s26, s12, 7
	v_readfirstlane_b32 s12, v18
	s_lshl_b32 s13, s11, 4
	s_and_b32 s13, s13, 0xffffff80
	s_and_b32 s23, s12, 64
	v_and_b32_e32 v19, 31, v18
	s_or_b32 s13, s13, s23
	v_lshlrev_b64 v[2:3], 14, v[2:3]
	v_or_b32_e32 v182, s13, v19
	v_lshl_add_u64 v[2:3], s[84:85], 0, v[2:3]
	v_addc_co_u32_e32 v15, vcc, 0, v15, vcc
	s_ashr_i32 s12, s12, 1
	v_ashrrev_i32_e32 v183, 31, v182
	v_lshl_add_u64 v[12:13], v[2:3], 0, v[128:129]
	global_load_dwordx4 v[0:3], v[0:1], off offset:2560
	s_nop 0
	global_load_dwordx4 v[4:7], v[12:13], off
	global_load_dwordx4 v[130:133], v[14:15], off offset:2560
	global_load_dwordx4 v[134:137], v[12:13], off offset:128
	s_lshl_b32 s13, s22, 8
	s_andn2_b32 s12, s12, 63
	v_lshl_add_u64 v[184:185], v[182:183], 0, s[54:55]
	s_add_i32 s12, s12, s13
	v_mad_u64_u32 v[10:11], s[22:23], v184, s25, v[10:11]
	v_bfe_u32 v196, v18, 5, 1
	v_mad_i32_i24 v11, v185, s25, v11
	s_ashr_i32 s13, s12, 31
	v_lshl_add_u64 v[10:11], s[12:13], 1, v[10:11]
	v_lshlrev_b32_e32 v12, 4, v196
	v_mov_b32_e32 v13, v129
	v_lshl_add_u64 v[10:11], v[10:11], 0, v[12:13]
	s_mov_b64 s[22:23], 0x1200
	v_add_co_u32_e32 v16, vcc, s48, v10
	v_lshl_add_u64 v[14:15], v[10:11], 0, s[22:23]
	s_nop 0
	v_addc_co_u32_e32 v17, vcc, 0, v11, vcc
	s_mov_b32 s23, 0x3d000
	v_add_co_u32_e32 v10, vcc, s23, v10
	global_load_dwordx4 v[138:141], v[14:15], off offset:32
	global_load_dwordx4 v[142:145], v[14:15], off offset:64
	global_load_dwordx4 v[146:149], v[16:17], off offset:512
	global_load_dwordx4 v[150:153], v[14:15], off offset:96
	v_addc_co_u32_e32 v11, vcc, 0, v11, vcc
	global_load_dwordx4 v[154:157], v[10:11], off offset:512
	global_load_dwordx4 v[158:161], v[10:11], off offset:544
	global_load_dwordx4 v[162:165], v[10:11], off offset:576
	global_load_dwordx4 v[166:169], v[10:11], off offset:608
	v_mul_lo_u32 v10, v8, s16
	v_lshlrev_b32_e32 v11, 1, v18
	v_lshrrev_b32_e32 v13, 1, v18
	v_add3_u32 v197, v10, v128, 0
	v_and_b32_e32 v11, 8, v11
	v_and_b32_e32 v13, 4, v13
	s_mov_b32 s15, s55
	v_mov_b32_e32 v32, 0
	s_mov_b32 s22, 0
	v_mov_b32_e32 v33, v32
	v_mov_b32_e32 v34, v32
	v_mov_b32_e32 v35, v32
	v_mov_b32_e32 v36, v32
	v_mov_b32_e32 v37, v32
	v_mov_b32_e32 v38, v32
	s_waitcnt vmcnt(11)
	ds_write_b128 v197, v[0:3]
	s_waitcnt vmcnt(10)
	ds_write_b128 v197, v[4:7] offset:36864
	s_waitcnt vmcnt(9)
	ds_write_b128 v197, v[130:133] offset:9216
	s_waitcnt vmcnt(8)
	ds_write_b128 v197, v[134:137] offset:46080
	v_and_b32_e32 v0, 19, v18
	v_or3_b32 v0, v0, v11, v13
	v_mul_u32_u24_e32 v0, 0x90, v0
	v_add3_u32 v198, 0, v0, v12
	v_mul_u32_u24_e32 v0, 0x90, v19
	v_add3_u32 v200, 0, v0, v12
	v_lshl_add_u64 v[0:1], v[8:9], 0, s[14:15]
	v_lshlrev_b64 v[0:1], 14, v[0:1]
	v_or_b32_e32 v0, v0, v128
	v_lshl_add_u64 v[186:187], s[4:5], 0, v[0:1]
	v_mad_i64_i32 v[0:1], s[14:15], v8, s25, 0
	v_mad_u64_u32 v[0:1], s[14:15], s24, v222, v[0:1]
	v_or3_b32 v0, v0, s26, v128
	v_lshl_add_u64 v[188:189], s[6:7], 0, v[0:1]
	v_mov_b32_e32 v39, v32
	v_mov_b32_e32 v40, v32
	v_mov_b32_e32 v41, v32
	v_mov_b32_e32 v42, v32
	v_mov_b32_e32 v43, v32
	v_mov_b32_e32 v44, v32
	v_mov_b32_e32 v45, v32
	v_mov_b32_e32 v46, v32
	v_mov_b32_e32 v47, v32
	v_mov_b32_e32 v48, v32
	v_mov_b32_e32 v49, v32
	v_mov_b32_e32 v50, v32
	v_mov_b32_e32 v51, v32
	v_mov_b32_e32 v52, v32
	v_mov_b32_e32 v53, v32
	v_mov_b32_e32 v54, v32
	v_mov_b32_e32 v55, v32
	v_mov_b32_e32 v56, v32
	v_mov_b32_e32 v57, v32
	v_mov_b32_e32 v58, v32
	v_mov_b32_e32 v59, v32
	v_mov_b32_e32 v60, v32
	v_mov_b32_e32 v61, v32
	v_mov_b32_e32 v62, v32
	v_mov_b32_e32 v63, v32
	v_mov_b32_e32 v0, v32
	v_mov_b32_e32 v1, v32
	v_mov_b32_e32 v2, v32
	v_mov_b32_e32 v3, v32
	v_mov_b32_e32 v4, v32
	v_mov_b32_e32 v5, v32
	v_mov_b32_e32 v6, v32
	v_mov_b32_e32 v7, v32
	v_mov_b32_e32 v8, v32
	v_mov_b32_e32 v9, v32
	v_mov_b32_e32 v10, v32
	v_mov_b32_e32 v11, v32
	v_mov_b32_e32 v12, v32
	v_mov_b32_e32 v13, v32
	v_mov_b32_e32 v14, v32
	v_mov_b32_e32 v15, v32
	v_mov_b32_e32 v16, v32
	v_mov_b32_e32 v17, v32
	v_mov_b32_e32 v18, v32
	v_mov_b32_e32 v19, v32
	v_mov_b32_e32 v20, v32
	v_mov_b32_e32 v21, v32
	v_mov_b32_e32 v22, v32
	v_mov_b32_e32 v23, v32
	v_mov_b32_e32 v24, v32
	v_mov_b32_e32 v25, v32
	v_mov_b32_e32 v26, v32
	v_mov_b32_e32 v27, v32
	v_mov_b32_e32 v28, v32
	v_mov_b32_e32 v29, v32
	v_mov_b32_e32 v30, v32
	v_mov_b32_e32 v31, v32
	v_mov_b32_e32 v190, v32
	v_mov_b32_e32 v191, v32
	s_waitcnt vmcnt(0) lgkmcnt(0)
	s_barrier
	ds_read_b128 v[226:229], v198 offset:0
	ds_read_b128 v[230:233], v198 offset:32
	ds_read_b128 v[234:237], v198 offset:64
	ds_read_b128 v[238:241], v198 offset:96
	ds_read_b128 v[202:205], v200 offset:36928
	ds_read_b128 v[192:195], v200 offset:41536
	ds_read_b128 v[210:213], v200 offset:36960
	ds_read_b128 v[242:245], v200 offset:41568
	v_mov_b32_e32 v214, 0
	v_mov_b32_e32 v215, 0
	v_mov_b32_e32 v96, 0
	v_mov_b32_e32 v97, 0
	v_mov_b32_e32 v98, 0
	v_mov_b32_e32 v99, 0
	v_mov_b32_e32 v100, 0
	v_mov_b32_e32 v101, 0
	v_mov_b32_e32 v102, 0
	v_mov_b32_e32 v103, 0
	v_mov_b32_e32 v112, 0
	v_mov_b32_e32 v113, 0
	v_mov_b32_e32 v114, 0
	v_mov_b32_e32 v115, 0
	v_mov_b32_e32 v116, 0
	v_mov_b32_e32 v117, 0
	v_mov_b32_e32 v118, 0
	v_mov_b32_e32 v119, 0
	v_mov_b32_e32 v126, 0
	v_mov_b32_e32 v127, 0
	v_mov_b32_e32 v128, v198
	s_waitcnt lgkmcnt(4)
	v_mfma_f32_32x32x16_bf16 v[64:79], v[226:229], v[146:149], 0
	v_mfma_f32_32x32x16_bf16 v[64:79], v[230:233], v[138:141], v[64:79]
	v_mfma_f32_32x32x16_bf16 v[64:79], v[234:237], v[142:145], v[64:79]
	v_mfma_f32_32x32x16_bf16 v[64:79], v[238:241], v[150:153], v[64:79]
	v_mfma_f32_32x32x16_bf16 v[80:95], v[238:241], v[166:169], 0
	ds_read_b128 v[238:241], v128 offset:4704
	v_mfma_f32_32x32x16_bf16 v[80:95], v[234:237], v[162:165], v[80:95]
	ds_read_b128 v[234:237], v128 offset:4672
	v_mfma_f32_32x32x16_bf16 v[80:95], v[230:233], v[158:161], v[80:95]
	ds_read_b128 v[230:233], v128 offset:4640
	v_mfma_f32_32x32x16_bf16 v[80:95], v[226:229], v[154:157], v[80:95]
	ds_read_b128 v[226:229], v128 offset:4608
	global_load_dwordx4 v[130:133], v[188:189], off
	global_load_dwordx4 v[134:137], v[186:187], off
	s_nop 7
; #define LAS __attribute__((address_space(3)))
; __device__ __forceinline__ unsigned pk_bf16(float lo, float hi) { return pg8::cvt_pk_bf16(lo, hi); }
; __device__ __forceinline__ void attn_c_unit(LAS unsigned char* lds, const bf16_t* proj, const bf16_t* vt, bf16_t* obuf, int b, int hk, int blk, float mref, unsigned long long* sg) {
;     ...
;         u32x4 pw0[4], pw1[4];
;         {
;             float ps = 0.f;
; #pragma unroll
;             for (int i = 0; i < 16; ++i) { s00[i] = __builtin_amdgcn_exp2f(s00[i]); s01[i] = __builtin_amdgcn_exp2f(s01[i]); ps += s00[i] + s01[i]; }
;             l0 += ps;
; #pragma unroll
;             for (int q = 0; q < 4; ++q) { pw0[0][q] = pk_bf16(s00[2 * q], s00[2 * q + 1]); pw0[1][q] = pk_bf16(s00[8 + 2 * q], s00[8 + 2 * q + 1]);
;                                           pw0[2][q] = pk_bf16(s01[2 * q], s01[2 * q + 1]); pw0[3][q] = pk_bf16(s01[8 + 2 * q], s01[8 + 2 * q + 1]); }
;         }
;         {
;             float ps = 0.f;
; #pragma unroll
;             for (int i = 0; i < 16; ++i) { s10[i] = __builtin_amdgcn_exp2f(s10[i]); s11[i] = __builtin_amdgcn_exp2f(s11[i]); ps += s10[i] + s11[i]; }
;             l1 += ps;
; #pragma unroll
;             for (int q = 0; q < 4; ++q) { pw1[0][q] = pk_bf16(s10[2 * q], s10[2 * q + 1]); pw1[1][q] = pk_bf16(s10[8 + 2 * q], s10[8 + 2 * q + 1]);
;                                           pw1[2][q] = pk_bf16(s11[2 * q], s11[2 * q + 1]); pw1[3][q] = pk_bf16(s11[8 + 2 * q], s11[8 + 2 * q + 1]); }
;         }
;         const LAS unsigned char* vb = lds + CV + buf * ATT_TILE + r * KP + 16 * h;
; #pragma unroll
;         for (int ks = 0; ks < 4; ++ks) {
;             const bf16x8 a0 = *(const LAS bf16x8*)(vb + 32 * ks), a1 = *(const LAS bf16x8*)(vb + 32 * KP + 32 * ks);
;             const bf16x8 p0 = __builtin_bit_cast(bf16x8, pw0[ks]), p1 = __builtin_bit_cast(bf16x8, pw1[ks]);
;             o00 = __builtin_amdgcn_mfma_f32_32x32x16_bf16(a0, p0, o00, 0, 0, 0);
;             o10 = __builtin_amdgcn_mfma_f32_32x32x16_bf16(a0, p1, o10, 0, 0, 0);
;             o01 = __builtin_amdgcn_mfma_f32_32x32x16_bf16(a1, p0, o01, 0, 0, 0);
;             o11 = __builtin_amdgcn_mfma_f32_32x32x16_bf16(a1, p1, o11, 0, 0, 0);
;         }
;         if (it + 2 < nT) { *(LAS u32x4*)(lds + CK + (buf ^ 2) * ATT_TILE + sdst) = kreg; *(LAS u32x4*)(lds + CV + (buf ^ 2) * ATT_TILE + sdst) = vreg; }
.Lc_top:
	s_waitcnt lgkmcnt(4)
	v_mfma_f32_32x32x16_bf16 v[32:47], v[202:205], v[96:99], v[32:47]
	v_exp_f32_e32 v64, v64
	v_exp_f32_e32 v65, v65
	v_add_f32_e32 v191, v191, v126
	v_add_f32_e32 v215, v215, v127
	v_cvt_pk_bf16_f32 v119, v126, v127
	v_mfma_f32_32x32x16_bf16 v[32:47], v[210:213], v[100:103], v[32:47]
	s_and_b32 s24, s22, 7
	s_mulk_i32 s24, 0x2400
	v_exp_f32_e32 v66, v66
	v_exp_f32_e32 v67, v67
	v_add_f32_e32 v190, v190, v64
	v_add_f32_e32 v214, v214, v65
	v_cvt_pk_bf16_f32 v64, v64, v65
	v_mfma_f32_32x32x16_bf16 v[0:15], v[210:213], v[116:119], v[0:15]
	v_add_u32_e32 v246, s24, v200
	v_exp_f32_e32 v68, v68
	v_exp_f32_e32 v69, v69
	v_add_f32_e32 v190, v190, v66
	v_add_f32_e32 v214, v214, v67
	v_cvt_pk_bf16_f32 v65, v66, v67
	v_mfma_f32_32x32x16_bf16 v[0:15], v[202:205], v[112:115], v[0:15]
	v_lshl_add_u64 v[186:187], v[186:187], 0, s[64:65]
	v_exp_f32_e32 v70, v70
	v_exp_f32_e32 v71, v71
	v_add_f32_e32 v190, v190, v68
	v_add_f32_e32 v214, v214, v69
	v_cvt_pk_bf16_f32 v66, v68, v69
	v_mfma_f32_32x32x16_bf16 v[16:31], v[192:195], v[112:115], v[16:31]
	v_lshl_add_u64 v[188:189], v[188:189], 0, s[68:69]
	v_exp_f32_e32 v72, v72
	v_exp_f32_e32 v73, v73
	v_add_f32_e32 v190, v190, v70
	v_add_f32_e32 v214, v214, v71
	v_cvt_pk_bf16_f32 v67, v70, v71
	v_mfma_f32_32x32x16_bf16 v[16:31], v[242:245], v[116:119], v[16:31]
	s_and_b32 s23, s22, 3
	s_mulk_i32 s23, 0x2400
	s_xor_b32 s23, s23, 0x4800
	v_exp_f32_e32 v74, v74
	v_exp_f32_e32 v75, v75
	v_add_f32_e32 v190, v190, v72
	v_add_f32_e32 v214, v214, v73
	v_cvt_pk_bf16_f32 v68, v72, v73
	v_mfma_f32_32x32x16_bf16 v[48:63], v[242:245], v[100:103], v[48:63]
	v_add_u32_e32 v201, s23, v197
	s_add_i32 s23, s22, 2
	s_and_b32 s23, s23, 7
	s_mulk_i32 s23, 0x2400
	v_exp_f32_e32 v76, v76
	v_exp_f32_e32 v77, v77
	v_add_f32_e32 v190, v190, v74
	v_add_f32_e32 v214, v214, v75
	v_cvt_pk_bf16_f32 v69, v74, v75
	v_mfma_f32_32x32x16_bf16 v[48:63], v[192:195], v[96:99], v[48:63]
	ds_read_b128 v[202:205], v246 offset:36864
	ds_read_b128 v[192:195], v246 offset:41472
	ds_read_b128 v[210:213], v246 offset:36896
	ds_read_b128 v[242:245], v246 offset:41504
	s_waitcnt lgkmcnt(4)
	v_exp_f32_e32 v78, v78
	v_exp_f32_e32 v79, v79
	v_add_f32_e32 v190, v190, v76
	v_add_f32_e32 v214, v214, v77
	v_cvt_pk_bf16_f32 v70, v76, v77
	v_mfma_f32_32x32x16_bf16 v[96:111], v[226:229], v[146:149], 0
	v_add_u32_e32 v206, s23, v197
	v_exp_f32_e32 v80, v80
	v_exp_f32_e32 v81, v81
	v_add_f32_e32 v190, v190, v78
	v_add_f32_e32 v214, v214, v79
	v_cvt_pk_bf16_f32 v71, v78, v79
	v_mfma_f32_32x32x16_bf16 v[96:111], v[230:233], v[138:141], v[96:111]
	s_cmpk_gt_u32 s22, 0x7d
	s_cbranch_scc1 .Lc_nostore
	s_waitcnt vmcnt(0)
	ds_write_b128 v201, v[130:133]
	ds_write_b128 v206, v[134:137] offset:36864

; #define LAS __attribute__((address_space(3)))
; __device__ __forceinline__ void attn_c_unit(LAS unsigned char* lds, const bf16_t* proj, const bf16_t* vt, bf16_t* obuf, int b, int hk, int blk, float mref, unsigned long long* sg) {
;     ...
;         for (int ks = 1; ks < 4; ++ks) {
;             const bf16x8 a0 = *(const LAS bf16x8*)(kb + 32 * ks), a1 = *(const LAS bf16x8*)(kb + 32 * KP + 32 * ks);
;             s00 = __builtin_amdgcn_mfma_f32_32x32x16_bf16(a0, qf[0][ks], s00, 0, 0, 0);
;             s10 = __builtin_amdgcn_mfma_f32_32x32x16_bf16(a0, qf[1][ks], s10, 0, 0, 0);
;             s01 = __builtin_amdgcn_mfma_f32_32x32x16_bf16(a1, qf[0][ks], s01, 0, 0, 0);
;             s11 = __builtin_amdgcn_mfma_f32_32x32x16_bf16(a1, qf[1][ks], s11, 0, 0, 0);
;         }
;         u32x4 pw0[4], pw1[4];
;         {
;             float ps = 0.f;
; #pragma unroll
;             for (int i = 0; i < 16; ++i) { s00[i] = __builtin_amdgcn_exp2f(s00[i]); s01[i] = __builtin_amdgcn_exp2f(s01[i]); ps += s00[i] + s01[i]; }
;             l0 += ps;
; #pragma unroll
;             for (int q = 0; q < 4; ++q) { pw0[0][q] = pk_bf16(s00[2 * q], s00[2 * q + 1]); pw0[1][q] = pk_bf16(s00[8 + 2 * q], s00[8 + 2 * q + 1]);
;                                           pw0[2][q] = pk_bf16(s01[2 * q], s01[2 * q + 1]); pw0[3][q] = pk_bf16(s01[8 + 2 * q], s01[8 + 2 * q + 1]); }
;         }
;         {
;             float ps = 0.f;
; #pragma unroll
;             for (int i = 0; i < 16; ++i) { s10[i] = __builtin_amdgcn_exp2f(s10[i]); s11[i] = __builtin_amdgcn_exp2f(s11[i]); ps += s10[i] + s11[i]; }
;             l1 += ps;
; #pragma unroll
;             for (int q = 0; q < 4; ++q) { pw1[0][q] = pk_bf16(s10[2 * q], s10[2 * q + 1]); pw1[1][q] = pk_bf16(s10[8 + 2 * q], s10[8 + 2 * q + 1]);
;                                           pw1[2][q] = pk_bf16(s11[2 * q], s11[2 * q + 1]); pw1[3][q] = pk_bf16(s11[8 + 2 * q], s11[8 + 2 * q + 1]); }
;         }
;         const LAS unsigned char* vb = lds + CV + buf * ATT_TILE + r * KP + 16 * h;
; #pragma unroll
;         for (int ks = 0; ks < 4; ++ks) {
;             const bf16x8 a0 = *(const LAS bf16x8*)(vb + 32 * ks), a1 = *(const LAS bf16x8*)(vb + 32 * KP + 32 * ks);
;             const bf16x8 p0 = __builtin_bit_cast(bf16x8, pw0[ks]), p1 = __builtin_bit_cast(bf16x8, pw1[ks]);
;             o00 = __builtin_amdgcn_mfma_f32_32x32x16_bf16(a0, p0, o00, 0, 0, 0);
.Lc_noload:
	v_exp_f32_e32 v82, v82
	v_exp_f32_e32 v83, v83
	v_add_f32_e32 v191, v191, v80
	v_add_f32_e32 v215, v215, v81
	v_cvt_pk_bf16_f32 v80, v80, v81
	v_mfma_f32_32x32x16_bf16 v[96:111], v[234:237], v[142:145], v[96:111]
	v_exp_f32_e32 v84, v84
	v_exp_f32_e32 v85, v85
	v_add_f32_e32 v191, v191, v82
	v_add_f32_e32 v215, v215, v83
	v_cvt_pk_bf16_f32 v81, v82, v83
	v_mfma_f32_32x32x16_bf16 v[96:111], v[238:241], v[150:153], v[96:111]
	v_exp_f32_e32 v86, v86
	v_exp_f32_e32 v87, v87
	v_add_f32_e32 v191, v191, v84
	v_add_f32_e32 v215, v215, v85
	v_cvt_pk_bf16_f32 v82, v84, v85
	v_mfma_f32_32x32x16_bf16 v[112:127], v[238:241], v[166:169], 0
	s_add_i32 s23, s22, 1
	s_and_b32 s23, s23, 3
	s_mulk_i32 s23, 0x2400
	v_exp_f32_e32 v88, v88
	v_exp_f32_e32 v89, v89
	v_add_f32_e32 v191, v191, v86
	v_add_f32_e32 v215, v215, v87
	v_cvt_pk_bf16_f32 v83, v86, v87
	v_mfma_f32_32x32x16_bf16 v[112:127], v[234:237], v[162:165], v[112:127]
	v_add_u32_e32 v128, s23, v198
	v_exp_f32_e32 v90, v90
	v_exp_f32_e32 v91, v91
	v_add_f32_e32 v191, v191, v88
	v_add_f32_e32 v215, v215, v89
	v_cvt_pk_bf16_f32 v84, v88, v89
	v_mfma_f32_32x32x16_bf16 v[112:127], v[230:233], v[158:161], v[112:127]
	v_exp_f32_e32 v92, v92
	v_exp_f32_e32 v93, v93
	v_add_f32_e32 v191, v191, v90
	v_add_f32_e32 v215, v215, v91
	v_cvt_pk_bf16_f32 v85, v90, v91
	v_mfma_f32_32x32x16_bf16 v[112:127], v[226:229], v[154:157], v[112:127]
	v_exp_f32_e32 v94, v94
	v_exp_f32_e32 v95, v95
	v_add_f32_e32 v191, v191, v92
	v_add_f32_e32 v215, v215, v93
	v_cvt_pk_bf16_f32 v86, v92, v93
	s_bitcmp0_b32 s22, 0
	s_cbranch_scc1 .Lc_nobar
	s_waitcnt lgkmcnt(0)
	s_barrier
.Lc_nobar:
	s_waitcnt lgkmcnt(0)
	v_mfma_f32_32x32x16_bf16 v[32:47], v[202:205], v[64:67], v[32:47]
	ds_read_b128 v[226:229], v128 offset:0
	ds_read_b128 v[230:233], v128 offset:32
	v_exp_f32_e32 v96, v96
	v_exp_f32_e32 v97, v97
	v_add_f32_e32 v191, v191, v94
	v_add_f32_e32 v215, v215, v95
	v_cvt_pk_bf16_f32 v87, v94, v95
	v_mfma_f32_32x32x16_bf16 v[32:47], v[210:213], v[68:71], v[32:47]
	ds_read_b128 v[234:237], v128 offset:64
	ds_read_b128 v[238:241], v128 offset:96
	v_exp_f32_e32 v98, v98
	v_exp_f32_e32 v99, v99
	v_add_f32_e32 v190, v190, v96
	v_add_f32_e32 v214, v214, v97
	v_cvt_pk_bf16_f32 v96, v96, v97
	v_mfma_f32_32x32x16_bf16 v[0:15], v[210:213], v[84:87], v[0:15]
	v_exp_f32_e32 v100, v100
	v_exp_f32_e32 v101, v101
	v_add_f32_e32 v190, v190, v98
	v_add_f32_e32 v214, v214, v99
	v_cvt_pk_bf16_f32 v97, v98, v99
	v_mfma_f32_32x32x16_bf16 v[0:15], v[202:205], v[80:83], v[0:15]
	v_exp_f32_e32 v102, v102
	v_exp_f32_e32 v103, v103
	v_add_f32_e32 v190, v190, v100
	v_add_f32_e32 v214, v214, v101
	v_cvt_pk_bf16_f32 v98, v100, v101
	v_mfma_f32_32x32x16_bf16 v[16:31], v[192:195], v[80:83], v[16:31]
	v_exp_f32_e32 v104, v104
	v_exp_f32_e32 v105, v105
	v_add_f32_e32 v190, v190, v102
	v_add_f32_e32 v214, v214, v103
	v_cvt_pk_bf16_f32 v99, v102, v103
	v_mfma_f32_32x32x16_bf16 v[16:31], v[242:245], v[84:87], v[16:31]
	v_exp_f32_e32 v106, v106
	v_exp_f32_e32 v107, v107
	v_add_f32_e32 v190, v190, v104
	v_add_f32_e32 v214, v214, v105
	v_cvt_pk_bf16_f32 v100, v104, v105
	v_mfma_f32_32x32x16_bf16 v[48:63], v[242:245], v[68:71], v[48:63]
	v_exp_f32_e32 v108, v108
	v_exp_f32_e32 v109, v109
	v_add_f32_e32 v190, v190, v106
	v_add_f32_e32 v214, v214, v107
	v_cvt_pk_bf16_f32 v101, v106, v107
	v_mfma_f32_32x32x16_bf16 v[48:63], v[192:195], v[64:67], v[48:63]
	ds_read_b128 v[202:205], v246 offset:36928
	ds_read_b128 v[192:195], v246 offset:41536
	ds_read_b128 v[210:213], v246 offset:36960
	ds_read_b128 v[242:245], v246 offset:41568
	s_waitcnt lgkmcnt(4)
	v_exp_f32_e32 v110, v110
	v_exp_f32_e32 v111, v111
	v_add_f32_e32 v190, v190, v108
	v_add_f32_e32 v214, v214, v109
	v_cvt_pk_bf16_f32 v102, v108, v109
	v_mfma_f32_32x32x16_bf16 v[64:79], v[226:229], v[146:149], 0
	v_exp_f32_e32 v112, v112
	v_exp_f32_e32 v113, v113
	v_add_f32_e32 v190, v190, v110
	v_add_f32_e32 v214, v214, v111
	v_cvt_pk_bf16_f32 v103, v110, v111
	v_mfma_f32_32x32x16_bf16 v[64:79], v[230:233], v[138:141], v[64:79]
	v_exp_f32_e32 v114, v114
	v_exp_f32_e32 v115, v115
	v_add_f32_e32 v191, v191, v112
	v_add_f32_e32 v215, v215, v113
	v_cvt_pk_bf16_f32 v112, v112, v113
	v_mfma_f32_32x32x16_bf16 v[64:79], v[234:237], v[142:145], v[64:79]
	s_add_i32 s22, s22, 1
	v_exp_f32_e32 v116, v116
	v_exp_f32_e32 v117, v117
	v_add_f32_e32 v191, v191, v114
	v_add_f32_e32 v215, v215, v115
	v_cvt_pk_bf16_f32 v113, v114, v115
	v_mfma_f32_32x32x16_bf16 v[64:79], v[238:241], v[150:153], v[64:79]
	v_exp_f32_e32 v118, v118
	v_exp_f32_e32 v119, v119
	v_add_f32_e32 v191, v191, v116
	v_add_f32_e32 v215, v215, v117
	v_cvt_pk_bf16_f32 v114, v116, v117
	v_mfma_f32_32x32x16_bf16 v[80:95], v[238:241], v[166:169], 0
	ds_read_b128 v[238:241], v128 offset:4704
	v_exp_f32_e32 v120, v120
	v_exp_f32_e32 v121, v121
	v_add_f32_e32 v191, v191, v118
	v_add_f32_e32 v215, v215, v119
	v_cvt_pk_bf16_f32 v115, v118, v119
	v_mfma_f32_32x32x16_bf16 v[80:95], v[234:237], v[162:165], v[80:95]
	ds_read_b128 v[234:237], v128 offset:4672
	v_exp_f32_e32 v122, v122
	v_exp_f32_e32 v123, v123
	v_add_f32_e32 v191, v191, v120
	v_add_f32_e32 v215, v215, v121
	v_cvt_pk_bf16_f32 v116, v120, v121
	v_mfma_f32_32x32x16_bf16 v[80:95], v[230:233], v[158:161], v[80:95]
	ds_read_b128 v[230:233], v128 offset:4640
	v_exp_f32_e32 v124, v124
	v_exp_f32_e32 v125, v125
	v_add_f32_e32 v191, v191, v122
	v_add_f32_e32 v215, v215, v123
	v_cvt_pk_bf16_f32 v117, v122, v123
	v_mfma_f32_32x32x16_bf16 v[80:95], v[226:229], v[154:157], v[80:95]
	ds_read_b128 v[226:229], v128 offset:4608
	v_exp_f32_e32 v126, v126
	v_exp_f32_e32 v127, v127
	v_add_f32_e32 v191, v191, v124
	v_add_f32_e32 v215, v215, v125
	v_cvt_pk_bf16_f32 v118, v124, v125
	s_cmpk_eq_i32 s22, 0x80
	s_cbranch_scc0 .Lc_top
	s_waitcnt lgkmcnt(0)
	v_add_f32_e32 v191, v191, v126
	v_add_f32_e32 v215, v215, v127
	v_cvt_pk_bf16_f32 v119, v126, v127
	v_mfma_f32_32x32x16_bf16 v[32:47], v[202:205], v[96:99], v[32:47]
	v_mfma_f32_32x32x16_bf16 v[32:47], v[210:213], v[100:103], v[32:47]
	v_mfma_f32_32x32x16_bf16 v[0:15], v[210:213], v[116:119], v[0:15]
	v_mfma_f32_32x32x16_bf16 v[0:15], v[202:205], v[112:115], v[0:15]
	v_mfma_f32_32x32x16_bf16 v[16:31], v[192:195], v[112:115], v[16:31]
	v_mfma_f32_32x32x16_bf16 v[16:31], v[242:245], v[116:119], v[16:31]
	v_mfma_f32_32x32x16_bf16 v[48:63], v[242:245], v[100:103], v[48:63]
	v_mfma_f32_32x32x16_bf16 v[48:63], v[192:195], v[96:99], v[48:63]
	v_add_f32_e32 v190, v190, v214
	v_add_f32_e32 v191, v191, v215
	s_barrier
